# MLA compute block: one counted lgkmcnt wait per two fragment reads (25 instead of 44 waits)
# speedup vs baseline: 1.0097x; 1.0097x over previous
.LBB0_1483:
	s_add_i32 s53, s53, 1
	ds_read_b128 v[212:215], v165
	ds_read_b128 v[216:219], v165 offset:64
	ds_read_b128 v[220:223], v165 offset:128
	ds_read_b128 v[224:227], v165 offset:3584
	ds_read_b128 v[228:231], v165 offset:3648
	s_waitcnt lgkmcnt(3)
	v_mfma_f32_16x16x32_bf16 v[232:235], v[212:215], v[0:3], 0
	v_mfma_f32_16x16x32_bf16 v[240:243], v[212:215], v[12:15], 0
	ds_read_b128 v[212:215], v165 offset:3712
	v_mfma_f32_16x16x32_bf16 v[232:235], v[216:219], v[4:7], v[232:235]
	v_mfma_f32_16x16x32_bf16 v[240:243], v[216:219], v[16:19], v[240:243]
	ds_read_b128 v[216:219], v165 offset:7168
	s_waitcnt lgkmcnt(3)
	v_mfma_f32_16x16x32_bf16 v[232:235], v[220:223], v[8:11], v[232:235]
	v_mfma_f32_16x16x32_bf16 v[240:243], v[220:223], v[20:23], v[240:243]
	ds_read_b128 v[220:223], v165 offset:7232
	v_mfma_f32_16x16x32_bf16 v[236:239], v[224:227], v[0:3], 0
	v_mfma_f32_16x16x32_bf16 v[244:247], v[224:227], v[12:15], 0
	ds_read_b128 v[224:227], v165 offset:7296
	s_waitcnt lgkmcnt(3)
	v_mfma_f32_16x16x32_bf16 v[236:239], v[228:231], v[4:7], v[236:239]
	v_mfma_f32_16x16x32_bf16 v[244:247], v[228:231], v[16:19], v[244:247]
	ds_read_b128 v[228:231], v165 offset:10752
	v_mfma_f32_16x16x32_bf16 v[236:239], v[212:215], v[8:11], v[236:239]
	v_exp_f32_e32 v232, v232
	v_mfma_f32_16x16x32_bf16 v[244:247], v[212:215], v[20:23], v[244:247]
	v_exp_f32_e32 v233, v233
	ds_read_b128 v[212:215], v165 offset:10816
	s_waitcnt lgkmcnt(3)
	v_mfma_f32_16x16x32_bf16 v[168:171], v[216:219], v[0:3], 0
	v_exp_f32_e32 v234, v234
	v_mfma_f32_16x16x32_bf16 v[176:179], v[216:219], v[12:15], 0
	v_exp_f32_e32 v235, v235
	ds_read_b128 v[216:219], v165 offset:10880
	v_mfma_f32_16x16x32_bf16 v[168:171], v[220:223], v[4:7], v[168:171]
	v_cvt_pk_bf16_f32 v232, v232, v233
	v_cvt_pk_bf16_f32 v233, v234, v235
	v_mfma_f32_16x16x32_bf16 v[176:179], v[220:223], v[16:19], v[176:179]
	v_exp_f32_e32 v240, v240
	ds_read_b128 v[220:223], v160 offset:28672
	s_waitcnt lgkmcnt(3)
	v_mfma_f32_16x16x32_bf16 v[168:171], v[224:227], v[8:11], v[168:171]
	v_exp_f32_e32 v241, v241
	v_mfma_f32_16x16x32_bf16 v[176:179], v[224:227], v[20:23], v[176:179]
	v_exp_f32_e32 v242, v242
	ds_read_b128 v[224:227], v160 offset:33280
	v_mfma_f32_16x16x32_bf16 v[172:175], v[228:231], v[0:3], 0
	v_exp_f32_e32 v243, v243
	v_mfma_f32_16x16x32_bf16 v[108:111], v[228:231], v[12:15], 0
	v_cvt_pk_bf16_f32 v240, v240, v241
	v_cvt_pk_bf16_f32 v241, v242, v243
	ds_read_b128 v[228:231], v160 offset:37888
	s_waitcnt lgkmcnt(3)
	v_mfma_f32_16x16x32_bf16 v[172:175], v[212:215], v[4:7], v[172:175]
	v_exp_f32_e32 v236, v236
	v_mfma_f32_16x16x32_bf16 v[108:111], v[212:215], v[16:19], v[108:111]
	v_exp_f32_e32 v237, v237
	ds_read_b128 v[212:215], v160 offset:42496
	v_mfma_f32_16x16x32_bf16 v[172:175], v[216:219], v[8:11], v[172:175]
	v_exp_f32_e32 v238, v238
	v_mfma_f32_16x16x32_bf16 v[108:111], v[216:219], v[20:23], v[108:111]
	v_exp_f32_e32 v239, v239
	ds_read_b128 v[216:219], v160 offset:47104
	s_waitcnt lgkmcnt(3)
	v_cvt_pk_bf16_f32 v234, v236, v237
	v_cvt_pk_bf16_f32 v235, v238, v239
	v_exp_f32_e32 v244, v244
	v_exp_f32_e32 v245, v245
	v_mfma_f32_16x16x32_bf16 v[84:87], v[220:223], v[232:235], v[84:87]
	v_exp_f32_e32 v246, v246
	v_exp_f32_e32 v247, v247
	v_cvt_pk_bf16_f32 v242, v244, v245
	v_cvt_pk_bf16_f32 v243, v246, v247
	v_exp_f32_e32 v168, v168
	v_exp_f32_e32 v169, v169
	v_mfma_f32_16x16x32_bf16 v[68:71], v[220:223], v[240:243], v[68:71]
	v_exp_f32_e32 v170, v170
	ds_read_b128 v[220:223], v165 offset:14336
	v_mfma_f32_16x16x32_bf16 v[88:91], v[224:227], v[232:235], v[88:91]
	v_exp_f32_e32 v171, v171
	v_mfma_f32_16x16x32_bf16 v[72:75], v[224:227], v[240:243], v[72:75]
	v_cvt_pk_bf16_f32 v168, v168, v169
	v_cvt_pk_bf16_f32 v169, v170, v171
	ds_read_b128 v[224:227], v165 offset:14400
	s_waitcnt lgkmcnt(3)
	v_mfma_f32_16x16x32_bf16 v[92:95], v[228:231], v[232:235], v[92:95]
	v_exp_f32_e32 v176, v176
	v_mfma_f32_16x16x32_bf16 v[76:79], v[228:231], v[240:243], v[76:79]
	v_exp_f32_e32 v177, v177
	ds_read_b128 v[228:231], v165 offset:14464
	v_mfma_f32_16x16x32_bf16 v[96:99], v[212:215], v[232:235], v[96:99]
	v_exp_f32_e32 v178, v178
	v_mfma_f32_16x16x32_bf16 v[80:83], v[212:215], v[240:243], v[80:83]
	v_exp_f32_e32 v179, v179
	ds_read_b128 v[212:215], v165 offset:17920
	s_waitcnt lgkmcnt(3)
	v_mfma_f32_16x16x32_bf16 v[104:107], v[216:219], v[232:235], v[104:107]
	v_cvt_pk_bf16_f32 v176, v176, v177
	v_cvt_pk_bf16_f32 v177, v178, v179
	v_mfma_f32_16x16x32_bf16 v[100:103], v[216:219], v[240:243], v[100:103]
	v_exp_f32_e32 v172, v172
	ds_read_b128 v[216:219], v165 offset:17984
	v_mfma_f32_16x16x32_bf16 v[232:235], v[220:223], v[0:3], 0
	v_exp_f32_e32 v173, v173
	v_mfma_f32_16x16x32_bf16 v[240:243], v[220:223], v[12:15], 0
	v_exp_f32_e32 v174, v174
	ds_read_b128 v[220:223], v165 offset:18048
	s_waitcnt lgkmcnt(3)
	v_mfma_f32_16x16x32_bf16 v[232:235], v[224:227], v[4:7], v[232:235]
	v_exp_f32_e32 v175, v175
	v_mfma_f32_16x16x32_bf16 v[240:243], v[224:227], v[16:19], v[240:243]
	v_cvt_pk_bf16_f32 v170, v172, v173
	v_cvt_pk_bf16_f32 v171, v174, v175
	ds_read_b128 v[224:227], v160 offset:28736
	v_mfma_f32_16x16x32_bf16 v[232:235], v[228:231], v[8:11], v[232:235]
	v_exp_f32_e32 v108, v108
	v_mfma_f32_16x16x32_bf16 v[240:243], v[228:231], v[20:23], v[240:243]
	v_exp_f32_e32 v109, v109
	ds_read_b128 v[228:231], v160 offset:33344
	s_waitcnt lgkmcnt(3)
	v_mfma_f32_16x16x32_bf16 v[236:239], v[212:215], v[0:3], 0
	v_exp_f32_e32 v110, v110
	v_mfma_f32_16x16x32_bf16 v[244:247], v[212:215], v[12:15], 0
	v_exp_f32_e32 v111, v111
	ds_read_b128 v[212:215], v160 offset:37952
	v_mfma_f32_16x16x32_bf16 v[236:239], v[216:219], v[4:7], v[236:239]
	v_cvt_pk_bf16_f32 v178, v108, v109
	v_cvt_pk_bf16_f32 v179, v110, v111
	v_mfma_f32_16x16x32_bf16 v[244:247], v[216:219], v[16:19], v[244:247]
	v_exp_f32_e32 v232, v232
	ds_read_b128 v[216:219], v160 offset:42560
	s_waitcnt lgkmcnt(3)
	v_mfma_f32_16x16x32_bf16 v[236:239], v[220:223], v[8:11], v[236:239]
	v_exp_f32_e32 v233, v233
	v_mfma_f32_16x16x32_bf16 v[244:247], v[220:223], v[20:23], v[244:247]
	v_exp_f32_e32 v234, v234
	ds_read_b128 v[220:223], v160 offset:47168
	v_mfma_f32_16x16x32_bf16 v[84:87], v[224:227], v[168:171], v[84:87]
	v_exp_f32_e32 v235, v235
	v_mfma_f32_16x16x32_bf16 v[68:71], v[224:227], v[176:179], v[68:71]
	v_cvt_pk_bf16_f32 v232, v232, v233
	v_cvt_pk_bf16_f32 v233, v234, v235
	ds_read_b128 v[224:227], v165 offset:21504
	s_waitcnt lgkmcnt(3)
	v_mfma_f32_16x16x32_bf16 v[88:91], v[228:231], v[168:171], v[88:91]
	v_exp_f32_e32 v240, v240
	v_mfma_f32_16x16x32_bf16 v[72:75], v[228:231], v[176:179], v[72:75]
	v_exp_f32_e32 v241, v241
	ds_read_b128 v[228:231], v165 offset:21568
	v_mfma_f32_16x16x32_bf16 v[92:95], v[212:215], v[168:171], v[92:95]
	v_exp_f32_e32 v242, v242
	v_mfma_f32_16x16x32_bf16 v[76:79], v[212:215], v[176:179], v[76:79]
	v_exp_f32_e32 v243, v243
	ds_read_b128 v[212:215], v165 offset:21632
	s_waitcnt lgkmcnt(3)
	v_mfma_f32_16x16x32_bf16 v[96:99], v[216:219], v[168:171], v[96:99]
	v_cvt_pk_bf16_f32 v240, v240, v241
	v_cvt_pk_bf16_f32 v241, v242, v243
	v_mfma_f32_16x16x32_bf16 v[80:83], v[216:219], v[176:179], v[80:83]
	v_exp_f32_e32 v236, v236
	ds_read_b128 v[216:219], v165 offset:25088
	v_mfma_f32_16x16x32_bf16 v[104:107], v[220:223], v[168:171], v[104:107]
	v_exp_f32_e32 v237, v237
	v_mfma_f32_16x16x32_bf16 v[100:103], v[220:223], v[176:179], v[100:103]
	v_exp_f32_e32 v238, v238
	ds_read_b128 v[220:223], v165 offset:25152
	s_waitcnt lgkmcnt(3)
	v_mfma_f32_16x16x32_bf16 v[168:171], v[224:227], v[0:3], 0
	v_exp_f32_e32 v239, v239
	v_mfma_f32_16x16x32_bf16 v[176:179], v[224:227], v[12:15], 0
	v_cvt_pk_bf16_f32 v234, v236, v237
	v_cvt_pk_bf16_f32 v235, v238, v239
	ds_read_b128 v[224:227], v165 offset:25216
	v_mfma_f32_16x16x32_bf16 v[168:171], v[228:231], v[4:7], v[168:171]
	v_exp_f32_e32 v244, v244
	v_mfma_f32_16x16x32_bf16 v[176:179], v[228:231], v[16:19], v[176:179]
	v_exp_f32_e32 v245, v245
	ds_read_b128 v[228:231], v160 offset:28800
	s_waitcnt lgkmcnt(3)
	v_mfma_f32_16x16x32_bf16 v[168:171], v[212:215], v[8:11], v[168:171]
	v_exp_f32_e32 v246, v246
	v_mfma_f32_16x16x32_bf16 v[176:179], v[212:215], v[20:23], v[176:179]
	v_exp_f32_e32 v247, v247
	ds_read_b128 v[212:215], v160 offset:33408
	v_mfma_f32_16x16x32_bf16 v[172:175], v[216:219], v[0:3], 0
	v_cvt_pk_bf16_f32 v242, v244, v245
	v_cvt_pk_bf16_f32 v243, v246, v247
	v_mfma_f32_16x16x32_bf16 v[108:111], v[216:219], v[12:15], 0
	ds_read_b128 v[216:219], v160 offset:38016
	s_waitcnt lgkmcnt(3)
	v_mfma_f32_16x16x32_bf16 v[172:175], v[220:223], v[4:7], v[172:175]
	v_exp_f32_e32 v168, v168
	v_mfma_f32_16x16x32_bf16 v[108:111], v[220:223], v[16:19], v[108:111]
	v_exp_f32_e32 v169, v169
	ds_read_b128 v[220:223], v160 offset:42624
	v_mfma_f32_16x16x32_bf16 v[172:175], v[224:227], v[8:11], v[172:175]
	v_exp_f32_e32 v170, v170
	v_mfma_f32_16x16x32_bf16 v[108:111], v[224:227], v[20:23], v[108:111]
	v_exp_f32_e32 v171, v171
	ds_read_b128 v[224:227], v160 offset:47232
	s_waitcnt lgkmcnt(3)
	v_mfma_f32_16x16x32_bf16 v[84:87], v[228:231], v[232:235], v[84:87]
	v_cvt_pk_bf16_f32 v168, v168, v169
	v_cvt_pk_bf16_f32 v169, v170, v171
	v_mfma_f32_16x16x32_bf16 v[68:71], v[228:231], v[240:243], v[68:71]
	v_exp_f32_e32 v176, v176
	ds_read_b128 v[228:231], v160 offset:28864
	v_mfma_f32_16x16x32_bf16 v[88:91], v[212:215], v[232:235], v[88:91]
	v_exp_f32_e32 v177, v177
	v_mfma_f32_16x16x32_bf16 v[72:75], v[212:215], v[240:243], v[72:75]
	v_exp_f32_e32 v178, v178
	ds_read_b128 v[212:215], v160 offset:33472
	s_waitcnt lgkmcnt(3)
	v_mfma_f32_16x16x32_bf16 v[92:95], v[216:219], v[232:235], v[92:95]
	v_exp_f32_e32 v179, v179
	v_mfma_f32_16x16x32_bf16 v[76:79], v[216:219], v[240:243], v[76:79]
	v_cvt_pk_bf16_f32 v176, v176, v177
	v_cvt_pk_bf16_f32 v177, v178, v179
	ds_read_b128 v[216:219], v160 offset:38080
	v_mfma_f32_16x16x32_bf16 v[96:99], v[220:223], v[232:235], v[96:99]
	v_exp_f32_e32 v172, v172
	v_mfma_f32_16x16x32_bf16 v[80:83], v[220:223], v[240:243], v[80:83]
	v_exp_f32_e32 v173, v173
	ds_read_b128 v[220:223], v160 offset:42688
	s_waitcnt lgkmcnt(4)
	v_mfma_f32_16x16x32_bf16 v[104:107], v[224:227], v[232:235], v[104:107]
	v_exp_f32_e32 v174, v174
	v_mfma_f32_16x16x32_bf16 v[100:103], v[224:227], v[240:243], v[100:103]
	v_exp_f32_e32 v175, v175
	ds_read_b128 v[224:227], v160 offset:47296
	s_waitcnt lgkmcnt(4)
	v_cvt_pk_bf16_f32 v170, v172, v173
	v_cvt_pk_bf16_f32 v171, v174, v175
	v_exp_f32_e32 v108, v108
	v_exp_f32_e32 v109, v109
	v_mfma_f32_16x16x32_bf16 v[84:87], v[228:231], v[168:171], v[84:87]
	v_exp_f32_e32 v110, v110
	s_waitcnt lgkmcnt(3)
	v_mfma_f32_16x16x32_bf16 v[88:91], v[212:215], v[168:171], v[88:91]
	v_exp_f32_e32 v111, v111
	s_waitcnt lgkmcnt(2)
	v_mfma_f32_16x16x32_bf16 v[92:95], v[216:219], v[168:171], v[92:95]
	v_cvt_pk_bf16_f32 v178, v108, v109
	v_cvt_pk_bf16_f32 v179, v110, v111
	s_waitcnt lgkmcnt(1)
	v_mfma_f32_16x16x32_bf16 v[96:99], v[220:223], v[168:171], v[96:99]
	s_waitcnt lgkmcnt(0)
	v_mfma_f32_16x16x32_bf16 v[104:107], v[224:227], v[168:171], v[104:107]
	v_mfma_f32_16x16x32_bf16 v[68:71], v[228:231], v[176:179], v[68:71]
	v_mfma_f32_16x16x32_bf16 v[72:75], v[212:215], v[176:179], v[72:75]
	v_mfma_f32_16x16x32_bf16 v[76:79], v[216:219], v[176:179], v[76:79]
	v_mfma_f32_16x16x32_bf16 v[80:83], v[220:223], v[176:179], v[80:83]
	v_mfma_f32_16x16x32_bf16 v[100:103], v[224:227], v[176:179], v[100:103]
	s_cmp_eq_u32 s53, 34
	s_cbranch_scc1 .LBB0_1504
